# grid barrier: the XCD leader no longer waits for the ack of its own XGEN release atomic before rejoining its workgroup (7 in-loop sites)
# speedup vs baseline: 1.0068x; 1.0052x over previous
; __device__ __forceinline__ unsigned xb_ld(unsigned* p)              { return __hip_atomic_load(p, __ATOMIC_RELAXED, __HIP_MEMORY_SCOPE_AGENT); }
; __device__ __forceinline__ unsigned xb_add(unsigned* p, unsigned v) { return __hip_atomic_fetch_add(p, v, __ATOMIC_RELAXED, __HIP_MEMORY_SCOPE_AGENT); }
; #define XB_SPIN(cond, bar) do { unsigned _sp = 0; while (cond) { \
;     if ((++_sp & 255u) == 0u) { if (xb_ld(&(bar)[XB_TMO])) break; if (_sp > XB_SPIN_CAP) { atomicAdd(&(bar)[XB_TMO], 1u); break; } } } } while (0)
; __device__ __forceinline__ void xcd_barrier(const XcdBarrier& b) {
;     ...
;             __builtin_amdgcn_fence(__ATOMIC_ACQUIRE, "agent");
;             xb_add(&bar[XB_XGEN(b.x)], 1u);
;             asm volatile("s_waitcnt vmcnt(0)" ::: "memory");
;         } else {
;             XB_SPIN(xb_ld(&bar[XB_XGEN(b.x)]) == gen, bar);
;             __builtin_amdgcn_fence(__ATOMIC_ACQUIRE, "agent");
;             asm volatile("s_waitcnt vmcnt(0)" ::: "memory");
;         }
;     }
;     __syncthreads();
.LBB0_231:
	s_or_b64 exec, exec, s[8:9]
	s_nop 0

; __device__ __forceinline__ unsigned xb_ld(unsigned* p)              { return __hip_atomic_load(p, __ATOMIC_RELAXED, __HIP_MEMORY_SCOPE_AGENT); }
; __device__ __forceinline__ unsigned xb_add(unsigned* p, unsigned v) { return __hip_atomic_fetch_add(p, v, __ATOMIC_RELAXED, __HIP_MEMORY_SCOPE_AGENT); }
; #define XB_SPIN(cond, bar) do { unsigned _sp = 0; while (cond) { \
;     if ((++_sp & 255u) == 0u) { if (xb_ld(&(bar)[XB_TMO])) break; if (_sp > XB_SPIN_CAP) { atomicAdd(&(bar)[XB_TMO], 1u); break; } } } } while (0)
; __device__ __forceinline__ void xcd_barrier(const XcdBarrier& b) {
;     ...
;             __builtin_amdgcn_fence(__ATOMIC_ACQUIRE, "agent");
;             xb_add(&bar[XB_XGEN(b.x)], 1u);
;             asm volatile("s_waitcnt vmcnt(0)" ::: "memory");
;         } else {
;             XB_SPIN(xb_ld(&bar[XB_XGEN(b.x)]) == gen, bar);
;             __builtin_amdgcn_fence(__ATOMIC_ACQUIRE, "agent");
;             asm volatile("s_waitcnt vmcnt(0)" ::: "memory");
;         }
;     }
;     __syncthreads();
.LBB0_667:
	s_or_b64 exec, exec, s[10:11]
	s_nop 0

; __device__ __forceinline__ unsigned xb_ld(unsigned* p)              { return __hip_atomic_load(p, __ATOMIC_RELAXED, __HIP_MEMORY_SCOPE_AGENT); }
; __device__ __forceinline__ unsigned xb_add(unsigned* p, unsigned v) { return __hip_atomic_fetch_add(p, v, __ATOMIC_RELAXED, __HIP_MEMORY_SCOPE_AGENT); }
; #define XB_SPIN(cond, bar) do { unsigned _sp = 0; while (cond) { \
;     if ((++_sp & 255u) == 0u) { if (xb_ld(&(bar)[XB_TMO])) break; if (_sp > XB_SPIN_CAP) { atomicAdd(&(bar)[XB_TMO], 1u); break; } } } } while (0)
; __device__ __forceinline__ void xcd_barrier(const XcdBarrier& b) {
;     ...
;             __builtin_amdgcn_fence(__ATOMIC_ACQUIRE, "agent");
;             xb_add(&bar[XB_XGEN(b.x)], 1u);
;             asm volatile("s_waitcnt vmcnt(0)" ::: "memory");
;         } else {
;             XB_SPIN(xb_ld(&bar[XB_XGEN(b.x)]) == gen, bar);
;             __builtin_amdgcn_fence(__ATOMIC_ACQUIRE, "agent");
;             asm volatile("s_waitcnt vmcnt(0)" ::: "memory");
;         }
;     }
;     __syncthreads();
.LBB0_1262:
	s_or_b64 exec, exec, s[12:13]
	s_nop 0
